# mixer B differential-combine: bf16 pack via v_cvt_pk_bf16_f32 instead of the integer RNE bit trick (bit-identical)
# baseline (speedup 1.0000x reference)
; __device__ __forceinline__ unsigned pk2(float lo, float hi) { return f2bf(lo) | (f2bf(hi) << 16); }
; __device__ __forceinline__ float sum16(float v) { v = sum8(v); v += dppf<DPP_MIR>(v); return v; }
; __global__ void __launch_bounds__(NWAVES * 64, 2) encoder_fwd(Args args) {
;     ...
;                 for (int b4 = 0; b4 < 8; b4 += 4) {
;                     v4u a[4], b[4];
; #pragma unroll
;                     for (int k = 0; k < 4; ++k) { const size_t row = (size_t)(sb + q0 + (b4 + k) * 32 + crr); const bf16* p0 = OB + row * 1024 + 256 * h + 8 * csub; a[k] = *(const v4u*)p0; b[k] = *(const v4u*)(p0 + 128); }
; #pragma unroll
;                     for (int k = 0; k < 4; ++k) { const size_t row = (size_t)(sb + q0 + (b4 + k) * 32 + crr);
;                         float o[8] = {bflo(a[k].x) - lam * bflo(b[k].x), bfhi(a[k].x) - lam * bfhi(b[k].x), bflo(a[k].y) - lam * bflo(b[k].y), bfhi(a[k].y) - lam * bfhi(b[k].y),
;                                       bflo(a[k].z) - lam * bflo(b[k].z), bfhi(a[k].z) - lam * bfhi(b[k].z), bflo(a[k].w) - lam * bflo(b[k].w), bfhi(a[k].w) - lam * bfhi(b[k].w)};
;                         float ss = 0.f;
; #pragma unroll
;                         for (int i = 0; i < 8; ++i) ss += o[i] * o[i];
;                         ss = sum16(ss);
;                         const float r = __builtin_amdgcn_rsqf(ss * (1.f / 128.f) + EPSN) * (1.f - lam_init);
;                         v4u w; w.x = pk2(o[0] * r, o[1] * r); w.y = pk2(o[2] * r, o[3] * r); w.z = pk2(o[4] * r, o[5] * r); w.w = pk2(o[6] * r, o[7] * r);
;                         *(v4u*)(ATT + row * 1024 + 512 + 128 * h + 8 * csub) = w; }
;                 }
.LBB0_535:
	v_cndmask_b32_e64 v6, 0, 1, s[6:7]
	v_cmp_ne_u32_e32 vcc, 1, v6
	v_add_u32_e32 v6, s0, v1
	v_ashrrev_i32_e32 v7, 31, v6
	v_lshlrev_b64 v[40:41], 11, v[6:7]
	v_lshl_add_u64 v[12:13], v[2:3], 0, v[40:41]
	global_load_dwordx4 v[8:11], v[12:13], off
	s_nop 0
	global_load_dwordx4 v[12:15], v[12:13], off offset:256
	v_add_u32_e32 v16, 32, v6
	v_ashrrev_i32_e32 v17, 31, v16
	v_lshlrev_b64 v[42:43], 11, v[16:17]
	v_lshl_add_u64 v[20:21], v[2:3], 0, v[42:43]
	global_load_dwordx4 v[16:19], v[20:21], off
	s_nop 0
	global_load_dwordx4 v[20:23], v[20:21], off offset:256
	v_add_u32_e32 v24, 64, v6
	v_ashrrev_i32_e32 v25, 31, v24
	v_lshlrev_b64 v[44:45], 11, v[24:25]
	v_lshl_add_u64 v[28:29], v[2:3], 0, v[44:45]
	global_load_dwordx4 v[24:27], v[28:29], off
	s_nop 0
	global_load_dwordx4 v[28:31], v[28:29], off offset:256
	v_add_u32_e32 v6, 0x60, v6
	v_ashrrev_i32_e32 v7, 31, v6
	v_lshlrev_b64 v[6:7], 11, v[6:7]
	v_lshl_add_u64 v[36:37], v[2:3], 0, v[6:7]
	global_load_dwordx4 v[32:35], v[36:37], off
	s_nop 0
	global_load_dwordx4 v[36:39], v[36:37], off offset:256
	v_lshl_add_u64 v[6:7], v[4:5], 0, v[6:7]
	s_movk_i32 s0, 0x80
	s_mov_b64 s[6:7], 0
	s_and_b64 vcc, exec, vcc
	s_waitcnt vmcnt(7)
	v_lshlrev_b32_e32 v47, 16, v9
	v_lshlrev_b32_e32 v46, 16, v8
	s_waitcnt vmcnt(6)
	v_lshlrev_b32_e32 v49, 16, v13
	v_lshlrev_b32_e32 v48, 16, v12
	v_and_b32_e32 v9, 0xffff0000, v9
	v_and_b32_e32 v8, 0xffff0000, v8
	v_and_b32_e32 v13, 0xffff0000, v13
	v_and_b32_e32 v12, 0xffff0000, v12
	v_pk_fma_f32 v[46:47], s[10:11], v[48:49], v[46:47] neg_lo:[1,0,0] neg_hi:[1,0,0]
	v_pk_fma_f32 v[8:9], s[10:11], v[12:13], v[8:9] neg_lo:[1,0,0] neg_hi:[1,0,0]
	v_pk_mul_f32 v[12:13], v[46:47], v[46:47]
	v_pk_mul_f32 v[48:49], v[8:9], v[8:9]
	v_lshlrev_b32_e32 v51, 16, v11
	v_lshlrev_b32_e32 v50, 16, v10
	v_lshlrev_b32_e32 v53, 16, v15
	v_lshlrev_b32_e32 v52, 16, v14
	v_and_b32_e32 v11, 0xffff0000, v11
	v_and_b32_e32 v10, 0xffff0000, v10
	v_and_b32_e32 v15, 0xffff0000, v15
	v_and_b32_e32 v14, 0xffff0000, v14
	v_pk_fma_f32 v[50:51], s[10:11], v[52:53], v[50:51] neg_lo:[1,0,0] neg_hi:[1,0,0]
	v_pk_fma_f32 v[10:11], s[10:11], v[14:15], v[10:11] neg_lo:[1,0,0] neg_hi:[1,0,0]
	v_add_f32_e32 v12, v12, v48
	v_mov_b32_e32 v14, v50
	v_mov_b32_e32 v15, v10
	v_add_f32_e32 v12, v12, v13
	v_pk_mul_f32 v[14:15], v[14:15], v[14:15]
	v_add_f32_e32 v12, v12, v49
	v_mov_b32_e32 v52, v51
	v_mov_b32_e32 v53, v11
	v_add_f32_e32 v12, v12, v14
	v_pk_mul_f32 v[52:53], v[52:53], v[52:53]
	v_add_f32_e32 v12, v12, v15
	v_add_f32_e32 v12, v12, v52
	v_add_f32_e32 v12, v12, v53
	s_nop 1
	v_add_f32_dpp v12, v12, v12 quad_perm:[1,0,3,2] row_mask:0xf bank_mask:0xf bound_ctrl:1
	s_nop 1
	v_add_f32_dpp v12, v12, v12 quad_perm:[2,3,0,1] row_mask:0xf bank_mask:0xf bound_ctrl:1
	s_nop 1
	v_add_f32_dpp v12, v12, v12 row_half_mirror row_mask:0xf bank_mask:0xf bound_ctrl:1
	s_nop 1
	v_add_f32_dpp v12, v12, v12 row_mirror row_mask:0xf bank_mask:0xf bound_ctrl:1
	v_fmamk_f32 v12, v12, 0x3c000000, v241
	v_rsq_f32_e32 v12, v12
	s_nop 0
	v_mul_f32_e32 v12, v252, v12
	v_pk_mul_f32 v[8:9], v[8:9], v[12:13] op_sel_hi:[1,0]
	v_pk_mul_f32 v[10:11], v[10:11], v[12:13] op_sel_hi:[1,0]
	v_pk_mul_f32 v[14:15], v[46:47], v[12:13] op_sel_hi:[1,0]
	v_pk_mul_f32 v[46:47], v[50:51], v[12:13] op_sel_hi:[1,0]
	v_cvt_pk_bf16_f32 v11, v47, v11
	v_cvt_pk_bf16_f32 v10, v46, v10
	v_cvt_pk_bf16_f32 v9, v15, v9
	v_cvt_pk_bf16_f32 v8, v14, v8
	v_lshl_add_u64 v[12:13], v[4:5], 0, v[40:41]
	global_store_dwordx4 v[12:13], v[8:11], off offset:1024
	s_waitcnt vmcnt(5)
	v_and_b32_e32 v13, 0xffff0000, v21
	v_and_b32_e32 v12, 0xffff0000, v20
	v_lshlrev_b32_e32 v9, 16, v17
	v_lshlrev_b32_e32 v8, 16, v16
	v_lshlrev_b32_e32 v11, 16, v21
	v_lshlrev_b32_e32 v10, 16, v20
	v_pk_fma_f32 v[8:9], s[10:11], v[10:11], v[8:9] neg_lo:[1,0,0] neg_hi:[1,0,0]
	v_and_b32_e32 v11, 0xffff0000, v17
	v_and_b32_e32 v10, 0xffff0000, v16
	v_pk_fma_f32 v[10:11], s[10:11], v[12:13], v[10:11] neg_lo:[1,0,0] neg_hi:[1,0,0]
	v_lshlrev_b32_e32 v17, 16, v19
	v_lshlrev_b32_e32 v16, 16, v18
	v_lshlrev_b32_e32 v21, 16, v23
	v_lshlrev_b32_e32 v20, 16, v22
	v_pk_mul_f32 v[12:13], v[8:9], v[8:9]
	v_pk_mul_f32 v[14:15], v[10:11], v[10:11]
	v_pk_fma_f32 v[16:17], s[10:11], v[20:21], v[16:17] neg_lo:[1,0,0] neg_hi:[1,0,0]
	v_and_b32_e32 v19, 0xffff0000, v19
	v_and_b32_e32 v18, 0xffff0000, v18
	v_and_b32_e32 v21, 0xffff0000, v23
	v_and_b32_e32 v20, 0xffff0000, v22
	v_pk_fma_f32 v[18:19], s[10:11], v[20:21], v[18:19] neg_lo:[1,0,0] neg_hi:[1,0,0]
	v_add_f32_e32 v12, v12, v14
	v_mov_b32_e32 v20, v16
	v_mov_b32_e32 v21, v18
	v_add_f32_e32 v12, v12, v13
	v_pk_mul_f32 v[20:21], v[20:21], v[20:21]
	v_add_f32_e32 v12, v12, v15
	v_mov_b32_e32 v22, v17
	v_mov_b32_e32 v23, v19
	v_add_f32_e32 v12, v12, v20
	v_pk_mul_f32 v[22:23], v[22:23], v[22:23]
	v_add_f32_e32 v12, v12, v21
	v_add_f32_e32 v12, v12, v22
	v_add_f32_e32 v12, v12, v23
	s_waitcnt vmcnt(3)
; __device__ __forceinline__ unsigned pk2(float lo, float hi) { return f2bf(lo) | (f2bf(hi) << 16); }
; __device__ __forceinline__ float sum16(float v) { v = sum8(v); v += dppf<DPP_MIR>(v); return v; }
; __global__ void __launch_bounds__(NWAVES * 64, 2) encoder_fwd(Args args) {
;     ...
;                 for (int b4 = 0; b4 < 8; b4 += 4) {
;                     v4u a[4], b[4];
; #pragma unroll
;                     for (int k = 0; k < 4; ++k) { const size_t row = (size_t)(sb + q0 + (b4 + k) * 32 + crr); const bf16* p0 = OB + row * 1024 + 256 * h + 8 * csub; a[k] = *(const v4u*)p0; b[k] = *(const v4u*)(p0 + 128); }
; #pragma unroll
;                     for (int k = 0; k < 4; ++k) { const size_t row = (size_t)(sb + q0 + (b4 + k) * 32 + crr);
;                         float o[8] = {bflo(a[k].x) - lam * bflo(b[k].x), bfhi(a[k].x) - lam * bfhi(b[k].x), bflo(a[k].y) - lam * bflo(b[k].y), bfhi(a[k].y) - lam * bfhi(b[k].y),
;                                       bflo(a[k].z) - lam * bflo(b[k].z), bfhi(a[k].z) - lam * bfhi(b[k].z), bflo(a[k].w) - lam * bflo(b[k].w), bfhi(a[k].w) - lam * bfhi(b[k].w)};
;                         float ss = 0.f;
; #pragma unroll
;                         for (int i = 0; i < 8; ++i) ss += o[i] * o[i];
;                         ss = sum16(ss);
;                         const float r = __builtin_amdgcn_rsqf(ss * (1.f / 128.f) + EPSN) * (1.f - lam_init);
;                         v4u w; w.x = pk2(o[0] * r, o[1] * r); w.y = pk2(o[2] * r, o[3] * r); w.z = pk2(o[4] * r, o[5] * r); w.w = pk2(o[6] * r, o[7] * r);
;                         *(v4u*)(ATT + row * 1024 + 512 + 128 * h + 8 * csub) = w; }
;                 }
	v_and_b32_e32 v21, 0xffff0000, v31
	v_and_b32_e32 v20, 0xffff0000, v30
	v_add_f32_dpp v12, v12, v12 quad_perm:[1,0,3,2] row_mask:0xf bank_mask:0xf bound_ctrl:1
	s_nop 1
	v_add_f32_dpp v12, v12, v12 quad_perm:[2,3,0,1] row_mask:0xf bank_mask:0xf bound_ctrl:1
	s_nop 1
	v_add_f32_dpp v12, v12, v12 row_half_mirror row_mask:0xf bank_mask:0xf bound_ctrl:1
	s_nop 1
	v_add_f32_dpp v12, v12, v12 row_mirror row_mask:0xf bank_mask:0xf bound_ctrl:1
	v_fmamk_f32 v12, v12, 0x3c000000, v241
	v_rsq_f32_e32 v12, v12
	s_nop 0
	v_mul_f32_e32 v12, v252, v12
	v_pk_mul_f32 v[8:9], v[8:9], v[12:13] op_sel_hi:[1,0]
	v_pk_mul_f32 v[10:11], v[10:11], v[12:13] op_sel_hi:[1,0]
	v_pk_mul_f32 v[14:15], v[16:17], v[12:13] op_sel_hi:[1,0]
	v_pk_mul_f32 v[12:13], v[18:19], v[12:13] op_sel_hi:[1,0]
	v_cvt_pk_bf16_f32 v9, v9, v11
	v_cvt_pk_bf16_f32 v11, v15, v13
	v_cvt_pk_bf16_f32 v8, v8, v10
	v_cvt_pk_bf16_f32 v10, v14, v12
	v_lshl_add_u64 v[12:13], v[4:5], 0, v[42:43]
	global_store_dwordx4 v[12:13], v[8:11], off offset:1024
	v_and_b32_e32 v13, 0xffff0000, v29
	v_and_b32_e32 v12, 0xffff0000, v28
	v_lshlrev_b32_e32 v9, 16, v25
	v_lshlrev_b32_e32 v8, 16, v24
	v_lshlrev_b32_e32 v11, 16, v29
	v_lshlrev_b32_e32 v10, 16, v28
	v_pk_fma_f32 v[8:9], s[10:11], v[10:11], v[8:9] neg_lo:[1,0,0] neg_hi:[1,0,0]
	v_and_b32_e32 v11, 0xffff0000, v25
	v_and_b32_e32 v10, 0xffff0000, v24
	v_pk_fma_f32 v[10:11], s[10:11], v[12:13], v[10:11] neg_lo:[1,0,0] neg_hi:[1,0,0]
	v_lshlrev_b32_e32 v17, 16, v27
	v_lshlrev_b32_e32 v16, 16, v26
	v_lshlrev_b32_e32 v19, 16, v31
	v_lshlrev_b32_e32 v18, 16, v30
	v_pk_mul_f32 v[12:13], v[8:9], v[8:9]
	v_pk_mul_f32 v[14:15], v[10:11], v[10:11]
	v_pk_fma_f32 v[16:17], s[10:11], v[18:19], v[16:17] neg_lo:[1,0,0] neg_hi:[1,0,0]
	v_and_b32_e32 v19, 0xffff0000, v27
	v_and_b32_e32 v18, 0xffff0000, v26
	v_pk_fma_f32 v[18:19], s[10:11], v[20:21], v[18:19] neg_lo:[1,0,0] neg_hi:[1,0,0]
	v_add_f32_e32 v12, v12, v14
	v_mov_b32_e32 v20, v16
	v_mov_b32_e32 v21, v18
	v_add_f32_e32 v12, v12, v13
	v_pk_mul_f32 v[20:21], v[20:21], v[20:21]
	v_add_f32_e32 v12, v12, v15
	v_mov_b32_e32 v22, v17
	v_mov_b32_e32 v23, v19
	v_add_f32_e32 v12, v12, v20
	v_pk_mul_f32 v[22:23], v[22:23], v[22:23]
	v_add_f32_e32 v12, v12, v21
	v_add_f32_e32 v12, v12, v22
	v_add_f32_e32 v12, v12, v23
	s_waitcnt vmcnt(2)
	v_and_b32_e32 v21, 0xffff0000, v39
	v_and_b32_e32 v20, 0xffff0000, v38
	v_add_f32_dpp v12, v12, v12 quad_perm:[1,0,3,2] row_mask:0xf bank_mask:0xf bound_ctrl:1
	s_nop 1
	v_add_f32_dpp v12, v12, v12 quad_perm:[2,3,0,1] row_mask:0xf bank_mask:0xf bound_ctrl:1
	s_nop 1
	v_add_f32_dpp v12, v12, v12 row_half_mirror row_mask:0xf bank_mask:0xf bound_ctrl:1
	s_nop 1
	v_add_f32_dpp v12, v12, v12 row_mirror row_mask:0xf bank_mask:0xf bound_ctrl:1
	v_fmamk_f32 v12, v12, 0x3c000000, v241
	v_rsq_f32_e32 v12, v12
	s_nop 0
	v_mul_f32_e32 v12, v252, v12
	v_pk_mul_f32 v[8:9], v[8:9], v[12:13] op_sel_hi:[1,0]
	v_pk_mul_f32 v[10:11], v[10:11], v[12:13] op_sel_hi:[1,0]
	v_pk_mul_f32 v[14:15], v[16:17], v[12:13] op_sel_hi:[1,0]
	v_pk_mul_f32 v[12:13], v[18:19], v[12:13] op_sel_hi:[1,0]
	v_cvt_pk_bf16_f32 v9, v9, v11
	v_cvt_pk_bf16_f32 v11, v15, v13
	v_cvt_pk_bf16_f32 v8, v8, v10
	v_cvt_pk_bf16_f32 v10, v14, v12
	v_lshl_add_u64 v[12:13], v[4:5], 0, v[44:45]
	global_store_dwordx4 v[12:13], v[8:11], off offset:1024
	v_and_b32_e32 v13, 0xffff0000, v37
	v_and_b32_e32 v12, 0xffff0000, v36
	v_lshlrev_b32_e32 v9, 16, v33
	v_lshlrev_b32_e32 v8, 16, v32
	v_lshlrev_b32_e32 v11, 16, v37
	v_lshlrev_b32_e32 v10, 16, v36
	v_pk_fma_f32 v[8:9], s[10:11], v[10:11], v[8:9] neg_lo:[1,0,0] neg_hi:[1,0,0]
	v_and_b32_e32 v11, 0xffff0000, v33
	v_and_b32_e32 v10, 0xffff0000, v32
	v_pk_fma_f32 v[10:11], s[10:11], v[12:13], v[10:11] neg_lo:[1,0,0] neg_hi:[1,0,0]
	v_lshlrev_b32_e32 v17, 16, v35
	v_lshlrev_b32_e32 v16, 16, v34
	v_lshlrev_b32_e32 v19, 16, v39
	v_lshlrev_b32_e32 v18, 16, v38
	v_pk_mul_f32 v[12:13], v[8:9], v[8:9]
	v_pk_mul_f32 v[14:15], v[10:11], v[10:11]
	v_pk_fma_f32 v[16:17], s[10:11], v[18:19], v[16:17] neg_lo:[1,0,0] neg_hi:[1,0,0]
	v_and_b32_e32 v19, 0xffff0000, v35
	v_and_b32_e32 v18, 0xffff0000, v34
	v_pk_fma_f32 v[18:19], s[10:11], v[20:21], v[18:19] neg_lo:[1,0,0] neg_hi:[1,0,0]
	v_add_f32_e32 v12, v12, v14
	v_mov_b32_e32 v20, v16
	v_mov_b32_e32 v21, v18
	v_add_f32_e32 v12, v12, v13
	v_pk_mul_f32 v[20:21], v[20:21], v[20:21]
	v_add_f32_e32 v12, v12, v15
	v_mov_b32_e32 v22, v17
	v_mov_b32_e32 v23, v19
	v_add_f32_e32 v12, v12, v20
	v_pk_mul_f32 v[22:23], v[22:23], v[22:23]
	v_add_f32_e32 v12, v12, v21
	v_add_f32_e32 v12, v12, v22
	v_add_f32_e32 v12, v12, v23
	s_nop 1
	v_add_f32_dpp v12, v12, v12 quad_perm:[1,0,3,2] row_mask:0xf bank_mask:0xf bound_ctrl:1
	s_nop 1
	v_add_f32_dpp v12, v12, v12 quad_perm:[2,3,0,1] row_mask:0xf bank_mask:0xf bound_ctrl:1
	s_nop 1
	v_add_f32_dpp v12, v12, v12 row_half_mirror row_mask:0xf bank_mask:0xf bound_ctrl:1
	s_nop 1
	v_add_f32_dpp v12, v12, v12 row_mirror row_mask:0xf bank_mask:0xf bound_ctrl:1
	v_fmamk_f32 v12, v12, 0x3c000000, v241
	v_rsq_f32_e32 v12, v12
	s_nop 0
	v_mul_f32_e32 v12, v252, v12
	v_pk_mul_f32 v[8:9], v[8:9], v[12:13] op_sel_hi:[1,0]
	v_pk_mul_f32 v[10:11], v[10:11], v[12:13] op_sel_hi:[1,0]
	v_pk_mul_f32 v[14:15], v[16:17], v[12:13] op_sel_hi:[1,0]
	v_pk_mul_f32 v[12:13], v[18:19], v[12:13] op_sel_hi:[1,0]
	v_cvt_pk_bf16_f32 v9, v9, v11
	v_cvt_pk_bf16_f32 v11, v15, v13
	v_cvt_pk_bf16_f32 v8, v8, v10
	v_cvt_pk_bf16_f32 v10, v14, v12
	global_store_dwordx4 v[6:7], v[8:11], off offset:1024
	s_cbranch_vccz .LBB0_535
	s_and_b64 vcc, exec, s[72:73]
	s_mov_b32 s0, s16
	s_cbranch_vccz .LBB0_456
